# FFN-in GEMM loop: SGPR-base DMA addressing (16 fewer 64-bit VALU adds per iteration) and rebalanced DMA issue 4/4 per segment with re-derived vmcnt
# speedup vs baseline: 1.0141x; 1.0141x over previous
; #define PG8_STAGE(bufoff, gbase, voff) do { _Pragma("unroll") for (int _i = 0; _i < 2; ++_i) \
;         __builtin_amdgcn_global_load_lds((const unsigned*)((const char*)(gbase) + (voff)[_i]), (PG8_LAS unsigned*)(lds + (bufoff) + ldsw + _i * 8192), 16, 0, 0); } while (0)
; #define PG8_LDA(dst, b, h) do { _Pragma("unroll") for (int m = 0; m < 4; ++m) _Pragma("unroll") for (int k = 0; k < 2; ++k) dst[m][k] = *(const PG8_LAS bf16x8*)(lds + PG8_SA(b, h) + aoff + m * 2048 + k * 1024); } while (0)
; #define PG8_LDB(dst, b, h) do { _Pragma("unroll") for (int n = 0; n < 2; ++n) _Pragma("unroll") for (int k = 0; k < 2; ++k) dst[n][k] = *(const PG8_LAS bf16x8*)(lds + PG8_SB(b, h) + boff + n * 2048 + k * 1024); } while (0)
; #define PG8_MMA(ai, bj, At, Bt) do { __builtin_amdgcn_s_setprio(1); _Pragma("unroll") for (int m = 0; m < 4; ++m) _Pragma("unroll") for (int n = 0; n < 2; ++n) _Pragma("unroll") for (int k = 0; k < 2; ++k) \
;         acc[ai][bj][m][n] = __builtin_amdgcn_mfma_f32_16x16x32_bf16(Bt[n][k], At[m][k], acc[ai][bj][m][n], 0, 0, 0); __builtin_amdgcn_s_setprio(0); } while (0)
; #define PG8_WAIT_V(n) asm volatile("s_waitcnt vmcnt(" #n ")" ::: "memory")
; #define PG8_BAR __builtin_amdgcn_s_barrier()
; template <class Epi, class Sched, bool ALIGN_EPI = false, bool SP2 = false>
; __device__ __forceinline__ void gemm_phase(PG8_LAS unsigned char* lds, const Gemm g, const Sched& S, const Epi& E, int tid_in) {
;     ...
;         for (int t = t_beg; t < t_end; t += 2) {
;             const bool last = (t == nt - 2);
;             const char* a1 = cA + (size_t)(t + 1) * kstep;
;             const char* a2 = last ? nA : cA + (size_t)(t + 2) * kstep; const char* b2 = last ? nB : cB + (size_t)(t + 2) * kstep;
;             const char* a3 = a2 + kstep; const char* b3 = b2 + kstep;
;             if (last && has_next) S.a_ready(nxt);
;             if constexpr (SP2) {
;             PG8_LDB(B0, 0, 0); PG8_LDB(B1, 0, 1); PG8_SCHED; PG8_LDA(At, 0, 0); PG8_STAGE(PG8_SA(1, 1), a1 + hstep, voffA);
;             PG8_WAIT_V(8); PG8_WAIT_L(0); PG8_BAR; PG8_MMA(0, 0, At, B0); PG8_MMA(0, 1, At, B1); PG8_BAR; PG8_SCHED;
;             PG8_LDA(At, 0, 1); PG8_STAGE(PG8_SB(0, 0), b2, voffB); PG8_STAGE(PG8_SB(0, 1), b2 + hstep, voffB); PG8_STAGE(PG8_SA(0, 0), a2, voffA);
;             PG8_WAIT_V(8); PG8_WAIT_L(0); PG8_BAR; PG8_MMA(1, 0, At, B0); PG8_MMA(1, 1, At, B1); PG8_BAR; PG8_SCHED;
.LBB0_26:
	s_add_u32 s14, s42, 0xfff80080
	s_addc_u32 s15, s43, -1
	s_add_u32 s100, s42, 0xfff80000
	s_addc_u32 s101, s43, -1
	s_add_i32 s86, 0, 0x10000
	s_cmp_eq_u32 s85, 28
	s_cselect_b32 s15, s10, s15
	s_cselect_b32 s14, s11, s14
	v_add_u32_e32 v138, s86, v141
	s_cselect_b32 s45, s31, s84
	s_cselect_b32 s44, s35, s83
	s_add_i32 s88, 0, 0x14000
	s_add_u32 s98, s44, 0x80
	s_addc_u32 s99, s45, 0
	ds_read_b128 v[144:147], v138
	ds_read_b128 v[148:151], v138 offset:1024
	ds_read_b128 v[152:155], v138 offset:2048
	ds_read_b128 v[156:159], v138 offset:3072
	v_add_u32_e32 v138, s88, v141
	ds_read_b128 v[160:163], v138
	ds_read_b128 v[164:167], v138 offset:1024
	ds_read_b128 v[168:171], v138 offset:2048
	ds_read_b128 v[172:175], v138 offset:3072
	s_mov_b32 m0, s55
	ds_read_b128 v[176:179], v143
	ds_read_b128 v[180:183], v143 offset:1024
	ds_read_b128 v[184:187], v143 offset:2048
	ds_read_b128 v[188:191], v143 offset:3072
	ds_read_b128 v[212:215], v143 offset:4096
	ds_read_b128 v[216:219], v143 offset:5120
	ds_read_b128 v[220:223], v143 offset:6144
	ds_read_b128 v[224:227], v143 offset:7168
	global_load_lds_dwordx4 v132, s[100:101]
	s_mov_b32 m0, s56
	s_nop 0
	global_load_lds_dwordx4 v130, s[100:101]
	s_add_i32 m0, s51, 0xc000
	s_nop 0
	global_load_lds_dwordx4 v136, s[42:43]
	s_add_i32 m0, s51, 0xe000
	s_nop 0
	global_load_lds_dwordx4 v134, s[42:43]
	s_waitcnt vmcnt(8)
	s_waitcnt lgkmcnt(0)
	s_barrier
	s_setprio 1
	s_waitcnt lgkmcnt(0)
	v_mfma_f32_16x16x32_bf16 v[124:127], v[144:147], v[176:179], v[124:127]
	v_mfma_f32_16x16x32_bf16 v[112:115], v[152:155], v[176:179], v[112:115]
	v_mfma_f32_16x16x32_bf16 v[108:111], v[144:147], v[184:187], v[108:111]
	v_mfma_f32_16x16x32_bf16 v[96:99], v[152:155], v[184:187], v[96:99]
	v_mfma_f32_16x16x32_bf16 v[92:95], v[144:147], v[212:215], v[92:95]
	v_mfma_f32_16x16x32_bf16 v[80:83], v[152:155], v[212:215], v[80:83]
	v_mfma_f32_16x16x32_bf16 v[76:79], v[144:147], v[220:223], v[76:79]
	v_mfma_f32_16x16x32_bf16 v[64:67], v[152:155], v[220:223], v[64:67]
	v_mfma_f32_16x16x32_bf16 v[124:127], v[148:151], v[180:183], v[124:127]
	v_mfma_f32_16x16x32_bf16 v[112:115], v[156:159], v[180:183], v[112:115]
	v_mfma_f32_16x16x32_bf16 v[108:111], v[148:151], v[188:191], v[108:111]
	v_mfma_f32_16x16x32_bf16 v[96:99], v[156:159], v[188:191], v[96:99]
	v_mfma_f32_16x16x32_bf16 v[92:95], v[148:151], v[216:219], v[92:95]
	v_mfma_f32_16x16x32_bf16 v[80:83], v[156:159], v[216:219], v[80:83]
	v_mfma_f32_16x16x32_bf16 v[76:79], v[148:151], v[224:227], v[76:79]
	v_mfma_f32_16x16x32_bf16 v[64:67], v[156:159], v[224:227], v[64:67]
	s_setprio 0
	s_setprio 1
	v_mfma_f32_16x16x32_bf16 v[120:123], v[160:163], v[176:179], v[120:123]
	v_mfma_f32_16x16x32_bf16 v[116:119], v[168:171], v[176:179], v[116:119]
	v_mfma_f32_16x16x32_bf16 v[104:107], v[160:163], v[184:187], v[104:107]
	v_mfma_f32_16x16x32_bf16 v[100:103], v[168:171], v[184:187], v[100:103]
	v_mfma_f32_16x16x32_bf16 v[88:91], v[160:163], v[212:215], v[88:91]
	v_mfma_f32_16x16x32_bf16 v[84:87], v[168:171], v[212:215], v[84:87]
	v_mfma_f32_16x16x32_bf16 v[72:75], v[160:163], v[220:223], v[72:75]
	v_mfma_f32_16x16x32_bf16 v[68:71], v[168:171], v[220:223], v[68:71]
	v_mfma_f32_16x16x32_bf16 v[120:123], v[164:167], v[180:183], v[120:123]
	v_mfma_f32_16x16x32_bf16 v[116:119], v[172:175], v[180:183], v[116:119]
	v_mfma_f32_16x16x32_bf16 v[104:107], v[164:167], v[188:191], v[104:107]
	v_mfma_f32_16x16x32_bf16 v[100:103], v[172:175], v[188:191], v[100:103]
	v_mfma_f32_16x16x32_bf16 v[88:91], v[164:167], v[216:219], v[88:91]
	v_mfma_f32_16x16x32_bf16 v[84:87], v[172:175], v[216:219], v[84:87]
	v_mfma_f32_16x16x32_bf16 v[72:75], v[164:167], v[224:227], v[72:75]
	v_mfma_f32_16x16x32_bf16 v[68:71], v[172:175], v[224:227], v[68:71]
	s_setprio 0
	s_barrier
	s_add_i32 s86, s86, s46
	s_mov_b32 m0, s86
	ds_read_b128 v[176:179], v143 offset:16384
	ds_read_b128 v[180:183], v143 offset:17408
	ds_read_b128 v[184:187], v143 offset:18432
	ds_read_b128 v[188:191], v143 offset:19456
	ds_read_b128 v[212:215], v143 offset:20480
	ds_read_b128 v[216:219], v143 offset:21504
	ds_read_b128 v[220:223], v143 offset:22528
	ds_read_b128 v[224:227], v143 offset:23552
	global_load_lds_dwordx4 v192, s[44:45]
	s_add_i32 m0, s86, 0x2000
	s_add_u32 s86, s44, 0x80000
	s_addc_u32 s87, s45, 0
	s_add_i32 s88, s88, s46
	global_load_lds_dwordx4 v128, s[44:45]
	s_mov_b32 m0, s88
	s_nop 0
	global_load_lds_dwordx4 v192, s[86:87]
	s_add_i32 m0, s88, 0x2000
	s_nop 0
	global_load_lds_dwordx4 v128, s[86:87]
	s_waitcnt vmcnt(6)
	s_waitcnt lgkmcnt(0)
	s_barrier
; #define PG8_STAGE(bufoff, gbase, voff) do { _Pragma("unroll") for (int _i = 0; _i < 2; ++_i) \
;         __builtin_amdgcn_global_load_lds((const unsigned*)((const char*)(gbase) + (voff)[_i]), (PG8_LAS unsigned*)(lds + (bufoff) + ldsw + _i * 8192), 16, 0, 0); } while (0)
; #define PG8_LDA(dst, b, h) do { _Pragma("unroll") for (int m = 0; m < 4; ++m) _Pragma("unroll") for (int k = 0; k < 2; ++k) dst[m][k] = *(const PG8_LAS bf16x8*)(lds + PG8_SA(b, h) + aoff + m * 2048 + k * 1024); } while (0)
; #define PG8_LDB(dst, b, h) do { _Pragma("unroll") for (int n = 0; n < 2; ++n) _Pragma("unroll") for (int k = 0; k < 2; ++k) dst[n][k] = *(const PG8_LAS bf16x8*)(lds + PG8_SB(b, h) + boff + n * 2048 + k * 1024); } while (0)
; #define PG8_MMA(ai, bj, At, Bt) do { __builtin_amdgcn_s_setprio(1); _Pragma("unroll") for (int m = 0; m < 4; ++m) _Pragma("unroll") for (int n = 0; n < 2; ++n) _Pragma("unroll") for (int k = 0; k < 2; ++k) \
;         acc[ai][bj][m][n] = __builtin_amdgcn_mfma_f32_16x16x32_bf16(Bt[n][k], At[m][k], acc[ai][bj][m][n], 0, 0, 0); __builtin_amdgcn_s_setprio(0); } while (0)
; #define PG8_WAIT_V(n) asm volatile("s_waitcnt vmcnt(" #n ")" ::: "memory")
; #define PG8_WAIT_L(n) asm volatile("s_waitcnt lgkmcnt(" #n ")" ::: "memory")
; #define PG8_BAR __builtin_amdgcn_s_barrier()
; #define PG8_SCHED __builtin_amdgcn_sched_barrier(0)
; template <class Epi, class Sched, bool ALIGN_EPI = false, bool SP2 = false>
; __device__ __forceinline__ void gemm_phase(PG8_LAS unsigned char* lds, const Gemm g, const Sched& S, const Epi& E, int tid_in) {
;     ...
;             PG8_WAIT_V(8); PG8_WAIT_L(0); PG8_BAR; PG8_MMA(1, 0, At, B0); PG8_MMA(1, 1, At, B1); PG8_BAR; PG8_SCHED;
;             PG8_LDB(B0, 1, 0); PG8_LDB(B1, 1, 1); PG8_SCHED; PG8_LDA(At, 1, 0); PG8_STAGE(PG8_SA(0, 1), a2 + hstep, voffA);
;             PG8_WAIT_V(8); PG8_WAIT_L(0); PG8_BAR; PG8_MMA(0, 0, At, B0); PG8_MMA(0, 1, At, B1); PG8_BAR; PG8_SCHED;
;             PG8_LDA(At, 1, 1); PG8_STAGE(PG8_SB(1, 0), b3, voffB); PG8_STAGE(PG8_SB(1, 1), b3 + hstep, voffB); PG8_STAGE(PG8_SA(1, 0), a3, voffA);
	s_setprio 1
	s_waitcnt lgkmcnt(0)
	v_mfma_f32_16x16x32_bf16 v[60:63], v[144:147], v[176:179], v[60:63]
	v_mfma_f32_16x16x32_bf16 v[48:51], v[152:155], v[176:179], v[48:51]
	v_mfma_f32_16x16x32_bf16 v[44:47], v[144:147], v[184:187], v[44:47]
	v_mfma_f32_16x16x32_bf16 v[32:35], v[152:155], v[184:187], v[32:35]
	v_mfma_f32_16x16x32_bf16 v[28:31], v[144:147], v[212:215], v[28:31]
	v_mfma_f32_16x16x32_bf16 v[16:19], v[152:155], v[212:215], v[16:19]
	v_mfma_f32_16x16x32_bf16 v[12:15], v[144:147], v[220:223], v[12:15]
	v_mfma_f32_16x16x32_bf16 v[4:7], v[152:155], v[220:223], v[4:7]
	v_mfma_f32_16x16x32_bf16 v[60:63], v[148:151], v[180:183], v[60:63]
	v_mfma_f32_16x16x32_bf16 v[48:51], v[156:159], v[180:183], v[48:51]
	v_mfma_f32_16x16x32_bf16 v[44:47], v[148:151], v[188:191], v[44:47]
	v_mfma_f32_16x16x32_bf16 v[32:35], v[156:159], v[188:191], v[32:35]
	v_mfma_f32_16x16x32_bf16 v[28:31], v[148:151], v[216:219], v[28:31]
	v_mfma_f32_16x16x32_bf16 v[16:19], v[156:159], v[216:219], v[16:19]
	v_mfma_f32_16x16x32_bf16 v[12:15], v[148:151], v[224:227], v[12:15]
	v_mfma_f32_16x16x32_bf16 v[4:7], v[156:159], v[224:227], v[4:7]
	s_setprio 0
	s_setprio 1
	v_mfma_f32_16x16x32_bf16 v[56:59], v[160:163], v[176:179], v[56:59]
	v_mfma_f32_16x16x32_bf16 v[52:55], v[168:171], v[176:179], v[52:55]
	v_mfma_f32_16x16x32_bf16 v[40:43], v[160:163], v[184:187], v[40:43]
	v_mfma_f32_16x16x32_bf16 v[36:39], v[168:171], v[184:187], v[36:39]
	v_mfma_f32_16x16x32_bf16 v[24:27], v[160:163], v[212:215], v[24:27]
	v_mfma_f32_16x16x32_bf16 v[20:23], v[168:171], v[212:215], v[20:23]
	v_mfma_f32_16x16x32_bf16 v[8:11], v[160:163], v[220:223], v[8:11]
	v_mfma_f32_16x16x32_bf16 v[0:3], v[168:171], v[220:223], v[0:3]
	v_mfma_f32_16x16x32_bf16 v[56:59], v[164:167], v[180:183], v[56:59]
	v_mfma_f32_16x16x32_bf16 v[52:55], v[172:175], v[180:183], v[52:55]
	v_mfma_f32_16x16x32_bf16 v[40:43], v[164:167], v[188:191], v[40:43]
	v_mfma_f32_16x16x32_bf16 v[36:39], v[172:175], v[188:191], v[36:39]
	v_mfma_f32_16x16x32_bf16 v[24:27], v[164:167], v[216:219], v[24:27]
	v_mfma_f32_16x16x32_bf16 v[20:23], v[172:175], v[216:219], v[20:23]
	v_mfma_f32_16x16x32_bf16 v[8:11], v[164:167], v[224:227], v[8:11]
	v_mfma_f32_16x16x32_bf16 v[0:3], v[172:175], v[224:227], v[0:3]
	s_setprio 0
	s_barrier
	s_add_i32 s86, 0, 0x18000
	s_add_i32 s87, 0, 0x1c000
	v_add_u32_e32 v156, s86, v141
	v_add_u32_e32 v172, s87, v141
	ds_read_b128 v[144:147], v156
	ds_read_b128 v[148:151], v156 offset:1024
	ds_read_b128 v[152:155], v156 offset:2048
	ds_read_b128 v[156:159], v156 offset:3072
	ds_read_b128 v[160:163], v172
	ds_read_b128 v[164:167], v172 offset:1024
	ds_read_b128 v[168:171], v172 offset:2048
	ds_read_b128 v[172:175], v172 offset:3072
	s_mov_b64 s[100:101], s[14:15]
	s_add_u32 s14, s14, 0x80000
	s_addc_u32 s15, s15, 0
	s_mov_b32 m0, s51
	ds_read_b128 v[176:179], v143 offset:32768
	ds_read_b128 v[180:183], v143 offset:33792
	ds_read_b128 v[184:187], v143 offset:34816
	ds_read_b128 v[188:191], v143 offset:35840
	ds_read_b128 v[212:215], v143 offset:36864
	ds_read_b128 v[216:219], v143 offset:37888
	ds_read_b128 v[220:223], v143 offset:38912
	ds_read_b128 v[224:227], v143 offset:39936
	global_load_lds_dwordx4 v132, s[100:101]
	s_mov_b32 m0, s52
	s_nop 0
	global_load_lds_dwordx4 v130, s[100:101]
	s_mov_b32 m0, s53
	s_nop 0
	global_load_lds_dwordx4 v132, s[14:15]
	s_mov_b32 m0, s54
	s_nop 0
	global_load_lds_dwordx4 v130, s[14:15]
	s_waitcnt vmcnt(8)
	s_waitcnt lgkmcnt(0)
	s_barrier
; #define PG8_STAGE(bufoff, gbase, voff) do { _Pragma("unroll") for (int _i = 0; _i < 2; ++_i) \
;         __builtin_amdgcn_global_load_lds((const unsigned*)((const char*)(gbase) + (voff)[_i]), (PG8_LAS unsigned*)(lds + (bufoff) + ldsw + _i * 8192), 16, 0, 0); } while (0)
; #define PG8_LDA(dst, b, h) do { _Pragma("unroll") for (int m = 0; m < 4; ++m) _Pragma("unroll") for (int k = 0; k < 2; ++k) dst[m][k] = *(const PG8_LAS bf16x8*)(lds + PG8_SA(b, h) + aoff + m * 2048 + k * 1024); } while (0)
; #define PG8_MMA(ai, bj, At, Bt) do { __builtin_amdgcn_s_setprio(1); _Pragma("unroll") for (int m = 0; m < 4; ++m) _Pragma("unroll") for (int n = 0; n < 2; ++n) _Pragma("unroll") for (int k = 0; k < 2; ++k) \
;         acc[ai][bj][m][n] = __builtin_amdgcn_mfma_f32_16x16x32_bf16(Bt[n][k], At[m][k], acc[ai][bj][m][n], 0, 0, 0); __builtin_amdgcn_s_setprio(0); } while (0)
; #define PG8_WAIT_V(n) asm volatile("s_waitcnt vmcnt(" #n ")" ::: "memory")
; #define PG8_WAIT_L(n) asm volatile("s_waitcnt lgkmcnt(" #n ")" ::: "memory")
; #define PG8_BAR __builtin_amdgcn_s_barrier()
; #define PG8_SCHED __builtin_amdgcn_sched_barrier(0)
; template <class Epi, class Sched, bool ALIGN_EPI = false, bool SP2 = false>
; __device__ __forceinline__ void gemm_phase(PG8_LAS unsigned char* lds, const Gemm g, const Sched& S, const Epi& E, int tid_in) {
;     ...
;             PG8_WAIT_V(8); PG8_WAIT_L(0); PG8_BAR; PG8_MMA(0, 0, At, B0); PG8_MMA(0, 1, At, B1); PG8_BAR; PG8_SCHED;
;             PG8_LDA(At, 1, 1); PG8_STAGE(PG8_SB(1, 0), b3, voffB); PG8_STAGE(PG8_SB(1, 1), b3 + hstep, voffB); PG8_STAGE(PG8_SA(1, 0), a3, voffA);
;             PG8_WAIT_V(8); PG8_WAIT_L(0); PG8_BAR; PG8_MMA(1, 0, At, B0); PG8_MMA(1, 1, At, B1); PG8_BAR; PG8_SCHED;
	s_setprio 1
	s_waitcnt lgkmcnt(0)
	v_mfma_f32_16x16x32_bf16 v[124:127], v[144:147], v[176:179], v[124:127]
	v_mfma_f32_16x16x32_bf16 v[112:115], v[152:155], v[176:179], v[112:115]
	v_mfma_f32_16x16x32_bf16 v[108:111], v[144:147], v[184:187], v[108:111]
	v_mfma_f32_16x16x32_bf16 v[96:99], v[152:155], v[184:187], v[96:99]
	v_mfma_f32_16x16x32_bf16 v[92:95], v[144:147], v[212:215], v[92:95]
	v_mfma_f32_16x16x32_bf16 v[80:83], v[152:155], v[212:215], v[80:83]
	v_mfma_f32_16x16x32_bf16 v[76:79], v[144:147], v[220:223], v[76:79]
	v_mfma_f32_16x16x32_bf16 v[64:67], v[152:155], v[220:223], v[64:67]
	v_mfma_f32_16x16x32_bf16 v[124:127], v[148:151], v[180:183], v[124:127]
	v_mfma_f32_16x16x32_bf16 v[112:115], v[156:159], v[180:183], v[112:115]
	v_mfma_f32_16x16x32_bf16 v[108:111], v[148:151], v[188:191], v[108:111]
	v_mfma_f32_16x16x32_bf16 v[96:99], v[156:159], v[188:191], v[96:99]
	v_mfma_f32_16x16x32_bf16 v[92:95], v[148:151], v[216:219], v[92:95]
	v_mfma_f32_16x16x32_bf16 v[80:83], v[156:159], v[216:219], v[80:83]
	v_mfma_f32_16x16x32_bf16 v[76:79], v[148:151], v[224:227], v[76:79]
	v_mfma_f32_16x16x32_bf16 v[64:67], v[156:159], v[224:227], v[64:67]
	s_setprio 0
	s_setprio 1
	v_mfma_f32_16x16x32_bf16 v[120:123], v[160:163], v[176:179], v[120:123]
	v_mfma_f32_16x16x32_bf16 v[116:119], v[168:171], v[176:179], v[116:119]
	v_mfma_f32_16x16x32_bf16 v[104:107], v[160:163], v[184:187], v[104:107]
	v_mfma_f32_16x16x32_bf16 v[100:103], v[168:171], v[184:187], v[100:103]
	v_mfma_f32_16x16x32_bf16 v[88:91], v[160:163], v[212:215], v[88:91]
	v_mfma_f32_16x16x32_bf16 v[84:87], v[168:171], v[212:215], v[84:87]
	v_mfma_f32_16x16x32_bf16 v[72:75], v[160:163], v[220:223], v[72:75]
	v_mfma_f32_16x16x32_bf16 v[68:71], v[168:171], v[220:223], v[68:71]
	v_mfma_f32_16x16x32_bf16 v[120:123], v[164:167], v[180:183], v[120:123]
	v_mfma_f32_16x16x32_bf16 v[116:119], v[172:175], v[180:183], v[116:119]
	v_mfma_f32_16x16x32_bf16 v[104:107], v[164:167], v[188:191], v[104:107]
	v_mfma_f32_16x16x32_bf16 v[100:103], v[172:175], v[188:191], v[100:103]
	v_mfma_f32_16x16x32_bf16 v[88:91], v[164:167], v[216:219], v[88:91]
	v_mfma_f32_16x16x32_bf16 v[84:87], v[172:175], v[216:219], v[84:87]
	v_mfma_f32_16x16x32_bf16 v[72:75], v[164:167], v[224:227], v[72:75]
	v_mfma_f32_16x16x32_bf16 v[68:71], v[172:175], v[224:227], v[68:71]
	s_setprio 0
	s_barrier
	s_add_i32 s14, s86, s46
	s_mov_b32 m0, s14
	ds_read_b128 v[176:179], v143 offset:49152
	ds_read_b128 v[180:183], v143 offset:50176
	ds_read_b128 v[184:187], v143 offset:51200
	ds_read_b128 v[188:191], v143 offset:52224
	ds_read_b128 v[212:215], v143 offset:53248
	ds_read_b128 v[216:219], v143 offset:54272
	ds_read_b128 v[220:223], v143 offset:55296
	ds_read_b128 v[224:227], v143 offset:56320
	global_load_lds_dwordx4 v192, s[98:99]
	s_add_i32 m0, s14, 0x2000
	s_add_u32 s14, s44, 0x80080
	s_addc_u32 s15, s45, 0
	s_add_i32 s44, s87, s46
	global_load_lds_dwordx4 v128, s[98:99]
	s_mov_b32 m0, s44
	s_nop 0
	global_load_lds_dwordx4 v192, s[14:15]
	s_add_i32 m0, s44, 0x2000
	s_nop 0
	global_load_lds_dwordx4 v128, s[14:15]
	s_waitcnt vmcnt(6)
	s_waitcnt lgkmcnt(0)
	s_barrier
	s_setprio 1
	s_waitcnt lgkmcnt(0)
	v_mfma_f32_16x16x32_bf16 v[60:63], v[144:147], v[176:179], v[60:63]
	v_mfma_f32_16x16x32_bf16 v[48:51], v[152:155], v[176:179], v[48:51]
	v_mfma_f32_16x16x32_bf16 v[44:47], v[144:147], v[184:187], v[44:47]
	v_mfma_f32_16x16x32_bf16 v[32:35], v[152:155], v[184:187], v[32:35]
	v_mfma_f32_16x16x32_bf16 v[28:31], v[144:147], v[212:215], v[28:31]
	v_mfma_f32_16x16x32_bf16 v[16:19], v[152:155], v[212:215], v[16:19]
	v_mfma_f32_16x16x32_bf16 v[12:15], v[144:147], v[220:223], v[12:15]
	v_mfma_f32_16x16x32_bf16 v[4:7], v[152:155], v[220:223], v[4:7]
	v_mfma_f32_16x16x32_bf16 v[60:63], v[148:151], v[180:183], v[60:63]
	v_mfma_f32_16x16x32_bf16 v[48:51], v[156:159], v[180:183], v[48:51]
	v_mfma_f32_16x16x32_bf16 v[44:47], v[148:151], v[188:191], v[44:47]
	v_mfma_f32_16x16x32_bf16 v[32:35], v[156:159], v[188:191], v[32:35]
	v_mfma_f32_16x16x32_bf16 v[28:31], v[148:151], v[216:219], v[28:31]
	v_mfma_f32_16x16x32_bf16 v[16:19], v[156:159], v[216:219], v[16:19]
	v_mfma_f32_16x16x32_bf16 v[12:15], v[148:151], v[224:227], v[12:15]
	v_mfma_f32_16x16x32_bf16 v[4:7], v[156:159], v[224:227], v[4:7]
	s_setprio 0
	s_setprio 1
	v_mfma_f32_16x16x32_bf16 v[56:59], v[160:163], v[176:179], v[56:59]
	v_mfma_f32_16x16x32_bf16 v[52:55], v[168:171], v[176:179], v[52:55]
	v_mfma_f32_16x16x32_bf16 v[40:43], v[160:163], v[184:187], v[40:43]
	v_mfma_f32_16x16x32_bf16 v[36:39], v[168:171], v[184:187], v[36:39]
	v_mfma_f32_16x16x32_bf16 v[24:27], v[160:163], v[212:215], v[24:27]
	v_mfma_f32_16x16x32_bf16 v[20:23], v[168:171], v[212:215], v[20:23]
	v_mfma_f32_16x16x32_bf16 v[8:11], v[160:163], v[220:223], v[8:11]
	v_mfma_f32_16x16x32_bf16 v[0:3], v[168:171], v[220:223], v[0:3]
	v_mfma_f32_16x16x32_bf16 v[56:59], v[164:167], v[180:183], v[56:59]
	v_mfma_f32_16x16x32_bf16 v[52:55], v[172:175], v[180:183], v[52:55]
	v_mfma_f32_16x16x32_bf16 v[40:43], v[164:167], v[188:191], v[40:43]
	v_mfma_f32_16x16x32_bf16 v[36:39], v[172:175], v[188:191], v[36:39]
	v_mfma_f32_16x16x32_bf16 v[24:27], v[164:167], v[216:219], v[24:27]
	v_mfma_f32_16x16x32_bf16 v[20:23], v[172:175], v[216:219], v[20:23]
	v_mfma_f32_16x16x32_bf16 v[8:11], v[164:167], v[224:227], v[8:11]
	v_mfma_f32_16x16x32_bf16 v[0:3], v[172:175], v[224:227], v[0:3]
	s_setprio 0
	s_barrier
	s_add_i32 s85, s85, 2
	s_add_u32 s83, s83, 0x100
	s_addc_u32 s84, s84, 0
	s_add_u32 s42, s42, 0x100
	s_addc_u32 s43, s43, 0
	s_cmp_gt_u32 s85, 29
	s_cbranch_scc0 .LBB0_26
	s_and_b64 vcc, exec, s[28:29]
	s_cbranch_vccz .LBB0_29
	s_barrier

; __global__ void __launch_bounds__(NWAVES * 64, 2) mk_fwd(Args args) {
	.amdhsa_kernel _Z6mk_fwd4Args
		.amdhsa_group_segment_fixed_size 0
		.amdhsa_private_segment_fixed_size 0
		.amdhsa_kernarg_size 440
		.amdhsa_user_sgpr_count 2
		.amdhsa_user_sgpr_dispatch_ptr 0
		.amdhsa_user_sgpr_queue_ptr 0
		.amdhsa_user_sgpr_kernarg_segment_ptr 1
		.amdhsa_user_sgpr_dispatch_id 0
		.amdhsa_user_sgpr_kernarg_preload_length 0
		.amdhsa_user_sgpr_kernarg_preload_offset 0
		.amdhsa_user_sgpr_private_segment_size 0
		.amdhsa_uses_dynamic_stack 0
		.amdhsa_enable_private_segment 0
		.amdhsa_system_sgpr_workgroup_id_x 1
		.amdhsa_system_sgpr_workgroup_id_y 0
		.amdhsa_system_sgpr_workgroup_id_z 0
		.amdhsa_system_sgpr_workgroup_info 0
		.amdhsa_system_vgpr_workitem_id 2
		.amdhsa_next_free_vgpr 256
		.amdhsa_next_free_sgpr 102
		.amdhsa_accum_offset 256
		.amdhsa_reserve_vcc 1
		.amdhsa_float_round_mode_32 0
		.amdhsa_float_round_mode_16_64 0
		.amdhsa_float_denorm_mode_32 3
		.amdhsa_float_denorm_mode_16_64 3
		.amdhsa_dx10_clamp 1
		.amdhsa_ieee_mode 1
		.amdhsa_fp16_overflow 0
		.amdhsa_tg_split 0
		.amdhsa_exception_fp_ieee_invalid_op 0
		.amdhsa_exception_fp_denorm_src 0
		.amdhsa_exception_fp_ieee_div_zero 0
		.amdhsa_exception_fp_ieee_overflow 0
		.amdhsa_exception_fp_ieee_underflow 0
		.amdhsa_exception_fp_ieee_inexact 0
		.amdhsa_exception_int_div_zero 0
	.end_amdhsa_kernel

; __global__ void __launch_bounds__(NWAVES * 64, 2) mk_fwd(Args args) {
amdhsa.kernels:
  - .agpr_count:     0
    .args:
      - .offset:         0
        .size:           184
        .value_kind:     by_value
      - .offset:         184
        .size:           4
        .value_kind:     hidden_block_count_x
      - .offset:         188
        .size:           4
        .value_kind:     hidden_block_count_y
      - .offset:         192
        .size:           4
        .value_kind:     hidden_block_count_z
      - .offset:         196
        .size:           2
        .value_kind:     hidden_group_size_x
      - .offset:         198
        .size:           2
        .value_kind:     hidden_group_size_y
      - .offset:         200
        .size:           2
        .value_kind:     hidden_group_size_z
      - .offset:         202
        .size:           2
        .value_kind:     hidden_remainder_x
      - .offset:         204
        .size:           2
        .value_kind:     hidden_remainder_y
      - .offset:         206
        .size:           2
        .value_kind:     hidden_remainder_z
      - .offset:         224
        .size:           8
        .value_kind:     hidden_global_offset_x
      - .offset:         232
        .size:           8
        .value_kind:     hidden_global_offset_y
      - .offset:         240
        .size:           8
        .value_kind:     hidden_global_offset_z
      - .offset:         248
        .size:           2
        .value_kind:     hidden_grid_dims
      - .offset:         272
        .size:           8
        .value_kind:     hidden_multigrid_sync_arg
      - .offset:         304
        .size:           4
        .value_kind:     hidden_dynamic_lds_size
    .group_segment_fixed_size: 0
    .kernarg_segment_align: 8
    .kernarg_segment_size: 440
    .language:       OpenCL C
    .language_version:
      - 2
      - 0
    .max_flat_workgroup_size: 512
    .name:           _Z6mk_fwd4Args
    .private_segment_fixed_size: 0
    .sgpr_count:     108
    .sgpr_spill_count: 96
    .symbol:         _Z6mk_fwd4Args.kd
    .uniform_work_group_size: 1
    .uses_dynamic_stack: false
    .vgpr_count:     256
    .vgpr_spill_count: 0
    .wavefront_size: 64
